# same as previous plus thread-0 mask reloaded from its saved lane before the deferred phase 3->4 wait
# baseline (speedup 1.0000x reference)
.Lp3d_chk:
	v_mov_b32_e32 v2, 0x24200
	ds_read_b32 v1, v2
	s_waitcnt lgkmcnt(0)
	v_readfirstlane_b32 s6, v1
	s_cmp_eq_u32 s6, 0
	s_cbranch_scc1 .Lp3d_go
	s_barrier
	v_readlane_b32 s94, v245, 34
	v_readlane_b32 s95, v245, 35
	s_and_saveexec_b64 s[2:3], s[94:95]
	s_cbranch_execz .Lp3d_wd
	ds_read_b32 v1, v2 offset:8
	s_waitcnt lgkmcnt(0)
	v_readfirstlane_b32 s10, v1
	ds_read_b32 v1, v2 offset:12
	s_waitcnt lgkmcnt(0)
	v_readfirstlane_b32 s11, v1
	ds_read_b32 v1, v2 offset:4
	s_waitcnt lgkmcnt(0)
	ds_write_b32 v2, v3
	s_mov_b32 s6, 0
	s_nop 4
